# P0 x->bf16 as row-per-wave streaming with the next row prefetched (16 KB of loads in flight per wave instead of 2 KB), on top of the fused P9
# baseline (speedup 1.0000x reference)
; __device__ __forceinline__ unsigned cvtpk(float lo, float hi) { f32x2_t v = {lo, hi}; bf16x2_t b = __builtin_convertvector(v, bf16x2_t); return __builtin_bit_cast(unsigned, b); }
; __global__ void __launch_bounds__(NTHREADS, 2) fwd_megakernel(Args args) {
;     ...
;         const size_t n8 = (size_t)MTOK * DM / 8;
;         for (size_t i = gt; i < n8; i += NGT) { const f32x4 a = *(const f32x4*)(x + i * 8), c = *(const f32x4*)(x + i * 8 + 4);
;             v4u o; o.x = cvtpk(a[0], a[1]); o.y = cvtpk(a[2], a[3]); o.z = cvtpk(c[0], c[1]); o.w = cvtpk(c[2], c[3]); *(v4u*)(XB + i * 8) = o; }
.LBB0_43:
	s_or_b64 exec, exec, s[0:1]
	s_waitcnt lgkmcnt(0)
	s_ashr_i32 s15, s42, 31
	s_mov_b32 s14, s42
	s_mov_b64 s[0:1], 0x800000
	s_lshl_b64 s[24:25], s[14:15], 9
	v_cmp_gt_u64_e32 vcc, s[0:1], v[4:5]
	s_and_saveexec_b64 s[0:1], vcc
	s_cbranch_execz .LBB0_46
	s_cmp_lg_u32 s42, 0x100
	s_cbranch_scc1 .Lxrow_generic
	v_readfirstlane_b32 s4, v178
	s_lshr_b32 s4, s4, 6
	s_lshl_b32 s5, s2, 3
	s_add_i32 s10, s4, s5
	v_mbcnt_lo_u32_b32 v1, -1, 0
	v_mbcnt_hi_u32_b32 v1, -1, v1
	v_lshlrev_b32_e32 v2, 4, v1
	v_add_u32_e32 v3, 0x1000, v2
	v_lshlrev_b32_e32 v16, 3, v1
	s_lshl_b32 s8, s10, 13
	s_add_u32 s4, s12, s8
	s_addc_u32 s5, s13, 0
	s_lshl_b32 s8, s10, 12
	s_add_u32 s8, s40, s8
	s_addc_u32 s9, s41, 0
	s_add_u32 s8, s8, 0x7c00000
	s_addc_u32 s9, s9, 0
	global_load_dwordx4 v[20:23], v2, s[4:5]
	global_load_dwordx4 v[24:27], v2, s[4:5] offset:1024
	global_load_dwordx4 v[28:31], v2, s[4:5] offset:2048
	global_load_dwordx4 v[32:35], v2, s[4:5] offset:3072
	global_load_dwordx4 v[36:39], v3, s[4:5]
	global_load_dwordx4 v[40:43], v3, s[4:5] offset:1024
	global_load_dwordx4 v[44:47], v3, s[4:5] offset:2048
	global_load_dwordx4 v[48:51], v3, s[4:5] offset:3072
	s_add_u32 s4, s4, 0x1000000
	s_addc_u32 s5, s5, 0
	global_load_dwordx4 v[52:55], v2, s[4:5]
	global_load_dwordx4 v[56:59], v2, s[4:5] offset:1024
	global_load_dwordx4 v[60:63], v2, s[4:5] offset:2048
	global_load_dwordx4 v[64:67], v2, s[4:5] offset:3072
	global_load_dwordx4 v[68:71], v3, s[4:5]
	global_load_dwordx4 v[72:75], v3, s[4:5] offset:1024
	global_load_dwordx4 v[76:79], v3, s[4:5] offset:2048
	global_load_dwordx4 v[80:83], v3, s[4:5] offset:3072
	s_add_u32 s4, s4, 0x1000000
	s_addc_u32 s5, s5, 0
	s_waitcnt vmcnt(8)
	v_cvt_pk_bf16_f32 v20, v20, v21
	v_cvt_pk_bf16_f32 v21, v22, v23
	v_cvt_pk_bf16_f32 v24, v24, v25
	v_cvt_pk_bf16_f32 v25, v26, v27
	v_cvt_pk_bf16_f32 v28, v28, v29
	v_cvt_pk_bf16_f32 v29, v30, v31
	v_cvt_pk_bf16_f32 v32, v32, v33
	v_cvt_pk_bf16_f32 v33, v34, v35
	v_cvt_pk_bf16_f32 v36, v36, v37
	v_cvt_pk_bf16_f32 v37, v38, v39
	v_cvt_pk_bf16_f32 v40, v40, v41
	v_cvt_pk_bf16_f32 v41, v42, v43
	v_cvt_pk_bf16_f32 v44, v44, v45
	v_cvt_pk_bf16_f32 v45, v46, v47
	v_cvt_pk_bf16_f32 v48, v48, v49
	v_cvt_pk_bf16_f32 v49, v50, v51
	global_store_dwordx2 v16, v[20:21], s[8:9]
	global_store_dwordx2 v16, v[24:25], s[8:9] offset:512
	global_store_dwordx2 v16, v[28:29], s[8:9] offset:1024
	global_store_dwordx2 v16, v[32:33], s[8:9] offset:1536
	global_store_dwordx2 v16, v[36:37], s[8:9] offset:2048
	global_store_dwordx2 v16, v[40:41], s[8:9] offset:2560
	global_store_dwordx2 v16, v[44:45], s[8:9] offset:3072
	global_store_dwordx2 v16, v[48:49], s[8:9] offset:3584
	s_add_u32 s8, s8, 0x800000
	s_addc_u32 s9, s9, 0
	global_load_dwordx4 v[20:23], v2, s[4:5]
	global_load_dwordx4 v[24:27], v2, s[4:5] offset:1024
	global_load_dwordx4 v[28:31], v2, s[4:5] offset:2048
	global_load_dwordx4 v[32:35], v2, s[4:5] offset:3072
	global_load_dwordx4 v[36:39], v3, s[4:5]
	global_load_dwordx4 v[40:43], v3, s[4:5] offset:1024
	global_load_dwordx4 v[44:47], v3, s[4:5] offset:2048
	global_load_dwordx4 v[48:51], v3, s[4:5] offset:3072
	s_add_u32 s4, s4, 0x1000000
	s_addc_u32 s5, s5, 0
	s_waitcnt vmcnt(16)
	v_cvt_pk_bf16_f32 v52, v52, v53
	v_cvt_pk_bf16_f32 v53, v54, v55
	v_cvt_pk_bf16_f32 v56, v56, v57
	v_cvt_pk_bf16_f32 v57, v58, v59
	v_cvt_pk_bf16_f32 v60, v60, v61
	v_cvt_pk_bf16_f32 v61, v62, v63
	v_cvt_pk_bf16_f32 v64, v64, v65
	v_cvt_pk_bf16_f32 v65, v66, v67
	v_cvt_pk_bf16_f32 v68, v68, v69
	v_cvt_pk_bf16_f32 v69, v70, v71
	v_cvt_pk_bf16_f32 v72, v72, v73
	v_cvt_pk_bf16_f32 v73, v74, v75
	v_cvt_pk_bf16_f32 v76, v76, v77
	v_cvt_pk_bf16_f32 v77, v78, v79
	v_cvt_pk_bf16_f32 v80, v80, v81
	v_cvt_pk_bf16_f32 v81, v82, v83
	global_store_dwordx2 v16, v[52:53], s[8:9]
	global_store_dwordx2 v16, v[56:57], s[8:9] offset:512
	global_store_dwordx2 v16, v[60:61], s[8:9] offset:1024
	global_store_dwordx2 v16, v[64:65], s[8:9] offset:1536
	global_store_dwordx2 v16, v[68:69], s[8:9] offset:2048
	global_store_dwordx2 v16, v[72:73], s[8:9] offset:2560
	global_store_dwordx2 v16, v[76:77], s[8:9] offset:3072
	global_store_dwordx2 v16, v[80:81], s[8:9] offset:3584
	s_add_u32 s8, s8, 0x800000
	s_addc_u32 s9, s9, 0
	global_load_dwordx4 v[52:55], v2, s[4:5]
	global_load_dwordx4 v[56:59], v2, s[4:5] offset:1024
	global_load_dwordx4 v[60:63], v2, s[4:5] offset:2048
	global_load_dwordx4 v[64:67], v2, s[4:5] offset:3072
	global_load_dwordx4 v[68:71], v3, s[4:5]
	global_load_dwordx4 v[72:75], v3, s[4:5] offset:1024
	global_load_dwordx4 v[76:79], v3, s[4:5] offset:2048
	global_load_dwordx4 v[80:83], v3, s[4:5] offset:3072
	s_add_u32 s4, s4, 0x1000000
	s_addc_u32 s5, s5, 0
	s_waitcnt vmcnt(16)
	v_cvt_pk_bf16_f32 v20, v20, v21
	v_cvt_pk_bf16_f32 v21, v22, v23
	v_cvt_pk_bf16_f32 v24, v24, v25
	v_cvt_pk_bf16_f32 v25, v26, v27
	v_cvt_pk_bf16_f32 v28, v28, v29
	v_cvt_pk_bf16_f32 v29, v30, v31
	v_cvt_pk_bf16_f32 v32, v32, v33
	v_cvt_pk_bf16_f32 v33, v34, v35
	v_cvt_pk_bf16_f32 v36, v36, v37
	v_cvt_pk_bf16_f32 v37, v38, v39
	v_cvt_pk_bf16_f32 v40, v40, v41
	v_cvt_pk_bf16_f32 v41, v42, v43
	v_cvt_pk_bf16_f32 v44, v44, v45
	v_cvt_pk_bf16_f32 v45, v46, v47
	v_cvt_pk_bf16_f32 v48, v48, v49
	v_cvt_pk_bf16_f32 v49, v50, v51
	global_store_dwordx2 v16, v[20:21], s[8:9]
	global_store_dwordx2 v16, v[24:25], s[8:9] offset:512
	global_store_dwordx2 v16, v[28:29], s[8:9] offset:1024
	global_store_dwordx2 v16, v[32:33], s[8:9] offset:1536
	global_store_dwordx2 v16, v[36:37], s[8:9] offset:2048
	global_store_dwordx2 v16, v[40:41], s[8:9] offset:2560
	global_store_dwordx2 v16, v[44:45], s[8:9] offset:3072
	global_store_dwordx2 v16, v[48:49], s[8:9] offset:3584
	s_add_u32 s8, s8, 0x800000
	s_addc_u32 s9, s9, 0
	global_load_dwordx4 v[20:23], v2, s[4:5]
	global_load_dwordx4 v[24:27], v2, s[4:5] offset:1024
	global_load_dwordx4 v[28:31], v2, s[4:5] offset:2048
	global_load_dwordx4 v[32:35], v2, s[4:5] offset:3072
	global_load_dwordx4 v[36:39], v3, s[4:5]
	global_load_dwordx4 v[40:43], v3, s[4:5] offset:1024
	global_load_dwordx4 v[44:47], v3, s[4:5] offset:2048
	global_load_dwordx4 v[48:51], v3, s[4:5] offset:3072
	s_add_u32 s4, s4, 0x1000000
	s_addc_u32 s5, s5, 0
	s_waitcnt vmcnt(16)
; __device__ __forceinline__ unsigned cvtpk(float lo, float hi) { f32x2_t v = {lo, hi}; bf16x2_t b = __builtin_convertvector(v, bf16x2_t); return __builtin_bit_cast(unsigned, b); }
; __global__ void __launch_bounds__(NTHREADS, 2) fwd_megakernel(Args args) {
;     ...
;         const size_t n8 = (size_t)MTOK * DM / 8;
;         for (size_t i = gt; i < n8; i += NGT) { const f32x4 a = *(const f32x4*)(x + i * 8), c = *(const f32x4*)(x + i * 8 + 4);
;             v4u o; o.x = cvtpk(a[0], a[1]); o.y = cvtpk(a[2], a[3]); o.z = cvtpk(c[0], c[1]); o.w = cvtpk(c[2], c[3]); *(v4u*)(XB + i * 8) = o; }
	v_cvt_pk_bf16_f32 v52, v52, v53
	v_cvt_pk_bf16_f32 v53, v54, v55
	v_cvt_pk_bf16_f32 v56, v56, v57
	v_cvt_pk_bf16_f32 v57, v58, v59
	v_cvt_pk_bf16_f32 v60, v60, v61
	v_cvt_pk_bf16_f32 v61, v62, v63
	v_cvt_pk_bf16_f32 v64, v64, v65
	v_cvt_pk_bf16_f32 v65, v66, v67
	v_cvt_pk_bf16_f32 v68, v68, v69
	v_cvt_pk_bf16_f32 v69, v70, v71
	v_cvt_pk_bf16_f32 v72, v72, v73
	v_cvt_pk_bf16_f32 v73, v74, v75
	v_cvt_pk_bf16_f32 v76, v76, v77
	v_cvt_pk_bf16_f32 v77, v78, v79
	v_cvt_pk_bf16_f32 v80, v80, v81
	v_cvt_pk_bf16_f32 v81, v82, v83
	global_store_dwordx2 v16, v[52:53], s[8:9]
	global_store_dwordx2 v16, v[56:57], s[8:9] offset:512
	global_store_dwordx2 v16, v[60:61], s[8:9] offset:1024
	global_store_dwordx2 v16, v[64:65], s[8:9] offset:1536
	global_store_dwordx2 v16, v[68:69], s[8:9] offset:2048
	global_store_dwordx2 v16, v[72:73], s[8:9] offset:2560
	global_store_dwordx2 v16, v[76:77], s[8:9] offset:3072
	global_store_dwordx2 v16, v[80:81], s[8:9] offset:3584
	s_add_u32 s8, s8, 0x800000
	s_addc_u32 s9, s9, 0
	global_load_dwordx4 v[52:55], v2, s[4:5]
	global_load_dwordx4 v[56:59], v2, s[4:5] offset:1024
	global_load_dwordx4 v[60:63], v2, s[4:5] offset:2048
	global_load_dwordx4 v[64:67], v2, s[4:5] offset:3072
	global_load_dwordx4 v[68:71], v3, s[4:5]
	global_load_dwordx4 v[72:75], v3, s[4:5] offset:1024
	global_load_dwordx4 v[76:79], v3, s[4:5] offset:2048
	global_load_dwordx4 v[80:83], v3, s[4:5] offset:3072
	s_add_u32 s4, s4, 0x1000000
	s_addc_u32 s5, s5, 0
	s_waitcnt vmcnt(16)
	v_cvt_pk_bf16_f32 v20, v20, v21
	v_cvt_pk_bf16_f32 v21, v22, v23
	v_cvt_pk_bf16_f32 v24, v24, v25
	v_cvt_pk_bf16_f32 v25, v26, v27
	v_cvt_pk_bf16_f32 v28, v28, v29
	v_cvt_pk_bf16_f32 v29, v30, v31
	v_cvt_pk_bf16_f32 v32, v32, v33
	v_cvt_pk_bf16_f32 v33, v34, v35
	v_cvt_pk_bf16_f32 v36, v36, v37
	v_cvt_pk_bf16_f32 v37, v38, v39
	v_cvt_pk_bf16_f32 v40, v40, v41
	v_cvt_pk_bf16_f32 v41, v42, v43
	v_cvt_pk_bf16_f32 v44, v44, v45
	v_cvt_pk_bf16_f32 v45, v46, v47
	v_cvt_pk_bf16_f32 v48, v48, v49
	v_cvt_pk_bf16_f32 v49, v50, v51
	global_store_dwordx2 v16, v[20:21], s[8:9]
	global_store_dwordx2 v16, v[24:25], s[8:9] offset:512
	global_store_dwordx2 v16, v[28:29], s[8:9] offset:1024
	global_store_dwordx2 v16, v[32:33], s[8:9] offset:1536
	global_store_dwordx2 v16, v[36:37], s[8:9] offset:2048
	global_store_dwordx2 v16, v[40:41], s[8:9] offset:2560
	global_store_dwordx2 v16, v[44:45], s[8:9] offset:3072
	global_store_dwordx2 v16, v[48:49], s[8:9] offset:3584
	s_add_u32 s8, s8, 0x800000
	s_addc_u32 s9, s9, 0
	global_load_dwordx4 v[20:23], v2, s[4:5]
	global_load_dwordx4 v[24:27], v2, s[4:5] offset:1024
	global_load_dwordx4 v[28:31], v2, s[4:5] offset:2048
	global_load_dwordx4 v[32:35], v2, s[4:5] offset:3072
	global_load_dwordx4 v[36:39], v3, s[4:5]
	global_load_dwordx4 v[40:43], v3, s[4:5] offset:1024
	global_load_dwordx4 v[44:47], v3, s[4:5] offset:2048
	global_load_dwordx4 v[48:51], v3, s[4:5] offset:3072
	s_add_u32 s4, s4, 0x1000000
	s_addc_u32 s5, s5, 0
	s_waitcnt vmcnt(16)
	v_cvt_pk_bf16_f32 v52, v52, v53
	v_cvt_pk_bf16_f32 v53, v54, v55
	v_cvt_pk_bf16_f32 v56, v56, v57
	v_cvt_pk_bf16_f32 v57, v58, v59
	v_cvt_pk_bf16_f32 v60, v60, v61
	v_cvt_pk_bf16_f32 v61, v62, v63
	v_cvt_pk_bf16_f32 v64, v64, v65
	v_cvt_pk_bf16_f32 v65, v66, v67
	v_cvt_pk_bf16_f32 v68, v68, v69
	v_cvt_pk_bf16_f32 v69, v70, v71
	v_cvt_pk_bf16_f32 v72, v72, v73
	v_cvt_pk_bf16_f32 v73, v74, v75
	v_cvt_pk_bf16_f32 v76, v76, v77
	v_cvt_pk_bf16_f32 v77, v78, v79
	v_cvt_pk_bf16_f32 v80, v80, v81
	v_cvt_pk_bf16_f32 v81, v82, v83
	global_store_dwordx2 v16, v[52:53], s[8:9]
	global_store_dwordx2 v16, v[56:57], s[8:9] offset:512
	global_store_dwordx2 v16, v[60:61], s[8:9] offset:1024
	global_store_dwordx2 v16, v[64:65], s[8:9] offset:1536
	global_store_dwordx2 v16, v[68:69], s[8:9] offset:2048
	global_store_dwordx2 v16, v[72:73], s[8:9] offset:2560
	global_store_dwordx2 v16, v[76:77], s[8:9] offset:3072
	global_store_dwordx2 v16, v[80:81], s[8:9] offset:3584
	s_add_u32 s8, s8, 0x800000
	s_addc_u32 s9, s9, 0
	global_load_dwordx4 v[52:55], v2, s[4:5]
	global_load_dwordx4 v[56:59], v2, s[4:5] offset:1024
	global_load_dwordx4 v[60:63], v2, s[4:5] offset:2048
	global_load_dwordx4 v[64:67], v2, s[4:5] offset:3072
	global_load_dwordx4 v[68:71], v3, s[4:5]
	global_load_dwordx4 v[72:75], v3, s[4:5] offset:1024
	global_load_dwordx4 v[76:79], v3, s[4:5] offset:2048
	global_load_dwordx4 v[80:83], v3, s[4:5] offset:3072
	s_add_u32 s4, s4, 0x1000000
	s_addc_u32 s5, s5, 0
	s_waitcnt vmcnt(16)
	v_cvt_pk_bf16_f32 v20, v20, v21
	v_cvt_pk_bf16_f32 v21, v22, v23
	v_cvt_pk_bf16_f32 v24, v24, v25
	v_cvt_pk_bf16_f32 v25, v26, v27
	v_cvt_pk_bf16_f32 v28, v28, v29
	v_cvt_pk_bf16_f32 v29, v30, v31
	v_cvt_pk_bf16_f32 v32, v32, v33
	v_cvt_pk_bf16_f32 v33, v34, v35
	v_cvt_pk_bf16_f32 v36, v36, v37
	v_cvt_pk_bf16_f32 v37, v38, v39
	v_cvt_pk_bf16_f32 v40, v40, v41
	v_cvt_pk_bf16_f32 v41, v42, v43
	v_cvt_pk_bf16_f32 v44, v44, v45
	v_cvt_pk_bf16_f32 v45, v46, v47
	v_cvt_pk_bf16_f32 v48, v48, v49
	v_cvt_pk_bf16_f32 v49, v50, v51
	global_store_dwordx2 v16, v[20:21], s[8:9]
	global_store_dwordx2 v16, v[24:25], s[8:9] offset:512
	global_store_dwordx2 v16, v[28:29], s[8:9] offset:1024
	global_store_dwordx2 v16, v[32:33], s[8:9] offset:1536
	global_store_dwordx2 v16, v[36:37], s[8:9] offset:2048
	global_store_dwordx2 v16, v[40:41], s[8:9] offset:2560
	global_store_dwordx2 v16, v[44:45], s[8:9] offset:3072
	global_store_dwordx2 v16, v[48:49], s[8:9] offset:3584
	s_add_u32 s8, s8, 0x800000
	s_addc_u32 s9, s9, 0
	global_load_dwordx4 v[20:23], v2, s[4:5]
	global_load_dwordx4 v[24:27], v2, s[4:5] offset:1024
	global_load_dwordx4 v[28:31], v2, s[4:5] offset:2048
	global_load_dwordx4 v[32:35], v2, s[4:5] offset:3072
	global_load_dwordx4 v[36:39], v3, s[4:5]
	global_load_dwordx4 v[40:43], v3, s[4:5] offset:1024
	global_load_dwordx4 v[44:47], v3, s[4:5] offset:2048
	global_load_dwordx4 v[48:51], v3, s[4:5] offset:3072
	s_add_u32 s4, s4, 0x1000000
	s_addc_u32 s5, s5, 0
	s_waitcnt vmcnt(16)
; __device__ __forceinline__ unsigned cvtpk(float lo, float hi) { f32x2_t v = {lo, hi}; bf16x2_t b = __builtin_convertvector(v, bf16x2_t); return __builtin_bit_cast(unsigned, b); }
; __global__ void __launch_bounds__(NTHREADS, 2) fwd_megakernel(Args args) {
;     ...
;         const size_t n8 = (size_t)MTOK * DM / 8;
;         for (size_t i = gt; i < n8; i += NGT) { const f32x4 a = *(const f32x4*)(x + i * 8), c = *(const f32x4*)(x + i * 8 + 4);
;             v4u o; o.x = cvtpk(a[0], a[1]); o.y = cvtpk(a[2], a[3]); o.z = cvtpk(c[0], c[1]); o.w = cvtpk(c[2], c[3]); *(v4u*)(XB + i * 8) = o; }
	v_cvt_pk_bf16_f32 v52, v52, v53
	v_cvt_pk_bf16_f32 v53, v54, v55
	v_cvt_pk_bf16_f32 v56, v56, v57
	v_cvt_pk_bf16_f32 v57, v58, v59
	v_cvt_pk_bf16_f32 v60, v60, v61
	v_cvt_pk_bf16_f32 v61, v62, v63
	v_cvt_pk_bf16_f32 v64, v64, v65
	v_cvt_pk_bf16_f32 v65, v66, v67
	v_cvt_pk_bf16_f32 v68, v68, v69
	v_cvt_pk_bf16_f32 v69, v70, v71
	v_cvt_pk_bf16_f32 v72, v72, v73
	v_cvt_pk_bf16_f32 v73, v74, v75
	v_cvt_pk_bf16_f32 v76, v76, v77
	v_cvt_pk_bf16_f32 v77, v78, v79
	v_cvt_pk_bf16_f32 v80, v80, v81
	v_cvt_pk_bf16_f32 v81, v82, v83
	global_store_dwordx2 v16, v[52:53], s[8:9]
	global_store_dwordx2 v16, v[56:57], s[8:9] offset:512
	global_store_dwordx2 v16, v[60:61], s[8:9] offset:1024
	global_store_dwordx2 v16, v[64:65], s[8:9] offset:1536
	global_store_dwordx2 v16, v[68:69], s[8:9] offset:2048
	global_store_dwordx2 v16, v[72:73], s[8:9] offset:2560
	global_store_dwordx2 v16, v[76:77], s[8:9] offset:3072
	global_store_dwordx2 v16, v[80:81], s[8:9] offset:3584
	s_add_u32 s8, s8, 0x800000
	s_addc_u32 s9, s9, 0
	global_load_dwordx4 v[52:55], v2, s[4:5]
	global_load_dwordx4 v[56:59], v2, s[4:5] offset:1024
	global_load_dwordx4 v[60:63], v2, s[4:5] offset:2048
	global_load_dwordx4 v[64:67], v2, s[4:5] offset:3072
	global_load_dwordx4 v[68:71], v3, s[4:5]
	global_load_dwordx4 v[72:75], v3, s[4:5] offset:1024
	global_load_dwordx4 v[76:79], v3, s[4:5] offset:2048
	global_load_dwordx4 v[80:83], v3, s[4:5] offset:3072
	s_add_u32 s4, s4, 0x1000000
	s_addc_u32 s5, s5, 0
	s_waitcnt vmcnt(16)
	v_cvt_pk_bf16_f32 v20, v20, v21
	v_cvt_pk_bf16_f32 v21, v22, v23
	v_cvt_pk_bf16_f32 v24, v24, v25
	v_cvt_pk_bf16_f32 v25, v26, v27
	v_cvt_pk_bf16_f32 v28, v28, v29
	v_cvt_pk_bf16_f32 v29, v30, v31
	v_cvt_pk_bf16_f32 v32, v32, v33
	v_cvt_pk_bf16_f32 v33, v34, v35
	v_cvt_pk_bf16_f32 v36, v36, v37
	v_cvt_pk_bf16_f32 v37, v38, v39
	v_cvt_pk_bf16_f32 v40, v40, v41
	v_cvt_pk_bf16_f32 v41, v42, v43
	v_cvt_pk_bf16_f32 v44, v44, v45
	v_cvt_pk_bf16_f32 v45, v46, v47
	v_cvt_pk_bf16_f32 v48, v48, v49
	v_cvt_pk_bf16_f32 v49, v50, v51
	global_store_dwordx2 v16, v[20:21], s[8:9]
	global_store_dwordx2 v16, v[24:25], s[8:9] offset:512
	global_store_dwordx2 v16, v[28:29], s[8:9] offset:1024
	global_store_dwordx2 v16, v[32:33], s[8:9] offset:1536
	global_store_dwordx2 v16, v[36:37], s[8:9] offset:2048
	global_store_dwordx2 v16, v[40:41], s[8:9] offset:2560
	global_store_dwordx2 v16, v[44:45], s[8:9] offset:3072
	global_store_dwordx2 v16, v[48:49], s[8:9] offset:3584
	s_add_u32 s8, s8, 0x800000
	s_addc_u32 s9, s9, 0
	global_load_dwordx4 v[20:23], v2, s[4:5]
	global_load_dwordx4 v[24:27], v2, s[4:5] offset:1024
	global_load_dwordx4 v[28:31], v2, s[4:5] offset:2048
	global_load_dwordx4 v[32:35], v2, s[4:5] offset:3072
	global_load_dwordx4 v[36:39], v3, s[4:5]
	global_load_dwordx4 v[40:43], v3, s[4:5] offset:1024
	global_load_dwordx4 v[44:47], v3, s[4:5] offset:2048
	global_load_dwordx4 v[48:51], v3, s[4:5] offset:3072
	s_add_u32 s4, s4, 0x1000000
	s_addc_u32 s5, s5, 0
	s_waitcnt vmcnt(16)
	v_cvt_pk_bf16_f32 v52, v52, v53
	v_cvt_pk_bf16_f32 v53, v54, v55
	v_cvt_pk_bf16_f32 v56, v56, v57
	v_cvt_pk_bf16_f32 v57, v58, v59
	v_cvt_pk_bf16_f32 v60, v60, v61
	v_cvt_pk_bf16_f32 v61, v62, v63
	v_cvt_pk_bf16_f32 v64, v64, v65
	v_cvt_pk_bf16_f32 v65, v66, v67
	v_cvt_pk_bf16_f32 v68, v68, v69
	v_cvt_pk_bf16_f32 v69, v70, v71
	v_cvt_pk_bf16_f32 v72, v72, v73
	v_cvt_pk_bf16_f32 v73, v74, v75
	v_cvt_pk_bf16_f32 v76, v76, v77
	v_cvt_pk_bf16_f32 v77, v78, v79
	v_cvt_pk_bf16_f32 v80, v80, v81
	v_cvt_pk_bf16_f32 v81, v82, v83
	global_store_dwordx2 v16, v[52:53], s[8:9]
	global_store_dwordx2 v16, v[56:57], s[8:9] offset:512
	global_store_dwordx2 v16, v[60:61], s[8:9] offset:1024
	global_store_dwordx2 v16, v[64:65], s[8:9] offset:1536
	global_store_dwordx2 v16, v[68:69], s[8:9] offset:2048
	global_store_dwordx2 v16, v[72:73], s[8:9] offset:2560
	global_store_dwordx2 v16, v[76:77], s[8:9] offset:3072
	global_store_dwordx2 v16, v[80:81], s[8:9] offset:3584
	s_add_u32 s8, s8, 0x800000
	s_addc_u32 s9, s9, 0
	global_load_dwordx4 v[52:55], v2, s[4:5]
	global_load_dwordx4 v[56:59], v2, s[4:5] offset:1024
	global_load_dwordx4 v[60:63], v2, s[4:5] offset:2048
	global_load_dwordx4 v[64:67], v2, s[4:5] offset:3072
	global_load_dwordx4 v[68:71], v3, s[4:5]
	global_load_dwordx4 v[72:75], v3, s[4:5] offset:1024
	global_load_dwordx4 v[76:79], v3, s[4:5] offset:2048
	global_load_dwordx4 v[80:83], v3, s[4:5] offset:3072
	s_add_u32 s4, s4, 0x1000000
	s_addc_u32 s5, s5, 0
	s_waitcnt vmcnt(16)
	v_cvt_pk_bf16_f32 v20, v20, v21
	v_cvt_pk_bf16_f32 v21, v22, v23
	v_cvt_pk_bf16_f32 v24, v24, v25
	v_cvt_pk_bf16_f32 v25, v26, v27
	v_cvt_pk_bf16_f32 v28, v28, v29
	v_cvt_pk_bf16_f32 v29, v30, v31
	v_cvt_pk_bf16_f32 v32, v32, v33
	v_cvt_pk_bf16_f32 v33, v34, v35
	v_cvt_pk_bf16_f32 v36, v36, v37
	v_cvt_pk_bf16_f32 v37, v38, v39
	v_cvt_pk_bf16_f32 v40, v40, v41
	v_cvt_pk_bf16_f32 v41, v42, v43
	v_cvt_pk_bf16_f32 v44, v44, v45
	v_cvt_pk_bf16_f32 v45, v46, v47
	v_cvt_pk_bf16_f32 v48, v48, v49
	v_cvt_pk_bf16_f32 v49, v50, v51
	global_store_dwordx2 v16, v[20:21], s[8:9]
	global_store_dwordx2 v16, v[24:25], s[8:9] offset:512
	global_store_dwordx2 v16, v[28:29], s[8:9] offset:1024
	global_store_dwordx2 v16, v[32:33], s[8:9] offset:1536
	global_store_dwordx2 v16, v[36:37], s[8:9] offset:2048
	global_store_dwordx2 v16, v[40:41], s[8:9] offset:2560
	global_store_dwordx2 v16, v[44:45], s[8:9] offset:3072
	global_store_dwordx2 v16, v[48:49], s[8:9] offset:3584
	s_add_u32 s8, s8, 0x800000
	s_addc_u32 s9, s9, 0
	global_load_dwordx4 v[20:23], v2, s[4:5]
	global_load_dwordx4 v[24:27], v2, s[4:5] offset:1024
	global_load_dwordx4 v[28:31], v2, s[4:5] offset:2048
	global_load_dwordx4 v[32:35], v2, s[4:5] offset:3072
	global_load_dwordx4 v[36:39], v3, s[4:5]
	global_load_dwordx4 v[40:43], v3, s[4:5] offset:1024
	global_load_dwordx4 v[44:47], v3, s[4:5] offset:2048
	global_load_dwordx4 v[48:51], v3, s[4:5] offset:3072
	s_add_u32 s4, s4, 0x1000000
	s_addc_u32 s5, s5, 0
	s_waitcnt vmcnt(16)
; __device__ __forceinline__ unsigned cvtpk(float lo, float hi) { f32x2_t v = {lo, hi}; bf16x2_t b = __builtin_convertvector(v, bf16x2_t); return __builtin_bit_cast(unsigned, b); }
; __global__ void __launch_bounds__(NTHREADS, 2) fwd_megakernel(Args args) {
;     ...
;         const size_t n8 = (size_t)MTOK * DM / 8;
;         for (size_t i = gt; i < n8; i += NGT) { const f32x4 a = *(const f32x4*)(x + i * 8), c = *(const f32x4*)(x + i * 8 + 4);
;             v4u o; o.x = cvtpk(a[0], a[1]); o.y = cvtpk(a[2], a[3]); o.z = cvtpk(c[0], c[1]); o.w = cvtpk(c[2], c[3]); *(v4u*)(XB + i * 8) = o; }
	v_cvt_pk_bf16_f32 v52, v52, v53
	v_cvt_pk_bf16_f32 v53, v54, v55
	v_cvt_pk_bf16_f32 v56, v56, v57
	v_cvt_pk_bf16_f32 v57, v58, v59
	v_cvt_pk_bf16_f32 v60, v60, v61
	v_cvt_pk_bf16_f32 v61, v62, v63
	v_cvt_pk_bf16_f32 v64, v64, v65
	v_cvt_pk_bf16_f32 v65, v66, v67
	v_cvt_pk_bf16_f32 v68, v68, v69
	v_cvt_pk_bf16_f32 v69, v70, v71
	v_cvt_pk_bf16_f32 v72, v72, v73
	v_cvt_pk_bf16_f32 v73, v74, v75
	v_cvt_pk_bf16_f32 v76, v76, v77
	v_cvt_pk_bf16_f32 v77, v78, v79
	v_cvt_pk_bf16_f32 v80, v80, v81
	v_cvt_pk_bf16_f32 v81, v82, v83
	global_store_dwordx2 v16, v[52:53], s[8:9]
	global_store_dwordx2 v16, v[56:57], s[8:9] offset:512
	global_store_dwordx2 v16, v[60:61], s[8:9] offset:1024
	global_store_dwordx2 v16, v[64:65], s[8:9] offset:1536
	global_store_dwordx2 v16, v[68:69], s[8:9] offset:2048
	global_store_dwordx2 v16, v[72:73], s[8:9] offset:2560
	global_store_dwordx2 v16, v[76:77], s[8:9] offset:3072
	global_store_dwordx2 v16, v[80:81], s[8:9] offset:3584
	s_add_u32 s8, s8, 0x800000
	s_addc_u32 s9, s9, 0
	global_load_dwordx4 v[52:55], v2, s[4:5]
	global_load_dwordx4 v[56:59], v2, s[4:5] offset:1024
	global_load_dwordx4 v[60:63], v2, s[4:5] offset:2048
	global_load_dwordx4 v[64:67], v2, s[4:5] offset:3072
	global_load_dwordx4 v[68:71], v3, s[4:5]
	global_load_dwordx4 v[72:75], v3, s[4:5] offset:1024
	global_load_dwordx4 v[76:79], v3, s[4:5] offset:2048
	global_load_dwordx4 v[80:83], v3, s[4:5] offset:3072
	s_add_u32 s4, s4, 0x1000000
	s_addc_u32 s5, s5, 0
	s_waitcnt vmcnt(16)
	v_cvt_pk_bf16_f32 v20, v20, v21
	v_cvt_pk_bf16_f32 v21, v22, v23
	v_cvt_pk_bf16_f32 v24, v24, v25
	v_cvt_pk_bf16_f32 v25, v26, v27
	v_cvt_pk_bf16_f32 v28, v28, v29
	v_cvt_pk_bf16_f32 v29, v30, v31
	v_cvt_pk_bf16_f32 v32, v32, v33
	v_cvt_pk_bf16_f32 v33, v34, v35
	v_cvt_pk_bf16_f32 v36, v36, v37
	v_cvt_pk_bf16_f32 v37, v38, v39
	v_cvt_pk_bf16_f32 v40, v40, v41
	v_cvt_pk_bf16_f32 v41, v42, v43
	v_cvt_pk_bf16_f32 v44, v44, v45
	v_cvt_pk_bf16_f32 v45, v46, v47
	v_cvt_pk_bf16_f32 v48, v48, v49
	v_cvt_pk_bf16_f32 v49, v50, v51
	global_store_dwordx2 v16, v[20:21], s[8:9]
	global_store_dwordx2 v16, v[24:25], s[8:9] offset:512
	global_store_dwordx2 v16, v[28:29], s[8:9] offset:1024
	global_store_dwordx2 v16, v[32:33], s[8:9] offset:1536
	global_store_dwordx2 v16, v[36:37], s[8:9] offset:2048
	global_store_dwordx2 v16, v[40:41], s[8:9] offset:2560
	global_store_dwordx2 v16, v[44:45], s[8:9] offset:3072
	global_store_dwordx2 v16, v[48:49], s[8:9] offset:3584
	s_add_u32 s8, s8, 0x800000
	s_addc_u32 s9, s9, 0
	global_load_dwordx4 v[20:23], v2, s[4:5]
	global_load_dwordx4 v[24:27], v2, s[4:5] offset:1024
	global_load_dwordx4 v[28:31], v2, s[4:5] offset:2048
	global_load_dwordx4 v[32:35], v2, s[4:5] offset:3072
	global_load_dwordx4 v[36:39], v3, s[4:5]
	global_load_dwordx4 v[40:43], v3, s[4:5] offset:1024
	global_load_dwordx4 v[44:47], v3, s[4:5] offset:2048
	global_load_dwordx4 v[48:51], v3, s[4:5] offset:3072
	s_add_u32 s4, s4, 0x1000000
	s_addc_u32 s5, s5, 0
	s_waitcnt vmcnt(16)
	v_cvt_pk_bf16_f32 v52, v52, v53
	v_cvt_pk_bf16_f32 v53, v54, v55
	v_cvt_pk_bf16_f32 v56, v56, v57
	v_cvt_pk_bf16_f32 v57, v58, v59
	v_cvt_pk_bf16_f32 v60, v60, v61
	v_cvt_pk_bf16_f32 v61, v62, v63
	v_cvt_pk_bf16_f32 v64, v64, v65
	v_cvt_pk_bf16_f32 v65, v66, v67
	v_cvt_pk_bf16_f32 v68, v68, v69
	v_cvt_pk_bf16_f32 v69, v70, v71
	v_cvt_pk_bf16_f32 v72, v72, v73
	v_cvt_pk_bf16_f32 v73, v74, v75
	v_cvt_pk_bf16_f32 v76, v76, v77
	v_cvt_pk_bf16_f32 v77, v78, v79
	v_cvt_pk_bf16_f32 v80, v80, v81
	v_cvt_pk_bf16_f32 v81, v82, v83
	global_store_dwordx2 v16, v[52:53], s[8:9]
	global_store_dwordx2 v16, v[56:57], s[8:9] offset:512
	global_store_dwordx2 v16, v[60:61], s[8:9] offset:1024
	global_store_dwordx2 v16, v[64:65], s[8:9] offset:1536
	global_store_dwordx2 v16, v[68:69], s[8:9] offset:2048
	global_store_dwordx2 v16, v[72:73], s[8:9] offset:2560
	global_store_dwordx2 v16, v[76:77], s[8:9] offset:3072
	global_store_dwordx2 v16, v[80:81], s[8:9] offset:3584
	s_add_u32 s8, s8, 0x800000
	s_addc_u32 s9, s9, 0
	global_load_dwordx4 v[52:55], v2, s[4:5]
	global_load_dwordx4 v[56:59], v2, s[4:5] offset:1024
	global_load_dwordx4 v[60:63], v2, s[4:5] offset:2048
	global_load_dwordx4 v[64:67], v2, s[4:5] offset:3072
	global_load_dwordx4 v[68:71], v3, s[4:5]
	global_load_dwordx4 v[72:75], v3, s[4:5] offset:1024
	global_load_dwordx4 v[76:79], v3, s[4:5] offset:2048
	global_load_dwordx4 v[80:83], v3, s[4:5] offset:3072
	s_add_u32 s4, s4, 0x1000000
	s_addc_u32 s5, s5, 0
	s_waitcnt vmcnt(16)
	v_cvt_pk_bf16_f32 v20, v20, v21
	v_cvt_pk_bf16_f32 v21, v22, v23
	v_cvt_pk_bf16_f32 v24, v24, v25
	v_cvt_pk_bf16_f32 v25, v26, v27
	v_cvt_pk_bf16_f32 v28, v28, v29
	v_cvt_pk_bf16_f32 v29, v30, v31
	v_cvt_pk_bf16_f32 v32, v32, v33
	v_cvt_pk_bf16_f32 v33, v34, v35
	v_cvt_pk_bf16_f32 v36, v36, v37
	v_cvt_pk_bf16_f32 v37, v38, v39
	v_cvt_pk_bf16_f32 v40, v40, v41
	v_cvt_pk_bf16_f32 v41, v42, v43
	v_cvt_pk_bf16_f32 v44, v44, v45
	v_cvt_pk_bf16_f32 v45, v46, v47
	v_cvt_pk_bf16_f32 v48, v48, v49
	v_cvt_pk_bf16_f32 v49, v50, v51
	global_store_dwordx2 v16, v[20:21], s[8:9]
	global_store_dwordx2 v16, v[24:25], s[8:9] offset:512
	global_store_dwordx2 v16, v[28:29], s[8:9] offset:1024
	global_store_dwordx2 v16, v[32:33], s[8:9] offset:1536
	global_store_dwordx2 v16, v[36:37], s[8:9] offset:2048
	global_store_dwordx2 v16, v[40:41], s[8:9] offset:2560
	global_store_dwordx2 v16, v[44:45], s[8:9] offset:3072
	global_store_dwordx2 v16, v[48:49], s[8:9] offset:3584
	s_add_u32 s8, s8, 0x800000
	s_addc_u32 s9, s9, 0
	s_waitcnt vmcnt(8)
	v_cvt_pk_bf16_f32 v52, v52, v53
	v_cvt_pk_bf16_f32 v53, v54, v55
	v_cvt_pk_bf16_f32 v56, v56, v57
	v_cvt_pk_bf16_f32 v57, v58, v59
	v_cvt_pk_bf16_f32 v60, v60, v61
	v_cvt_pk_bf16_f32 v61, v62, v63
	v_cvt_pk_bf16_f32 v64, v64, v65
	v_cvt_pk_bf16_f32 v65, v66, v67
	v_cvt_pk_bf16_f32 v68, v68, v69
	v_cvt_pk_bf16_f32 v69, v70, v71
	v_cvt_pk_bf16_f32 v72, v72, v73
	v_cvt_pk_bf16_f32 v73, v74, v75
	v_cvt_pk_bf16_f32 v76, v76, v77
	v_cvt_pk_bf16_f32 v77, v78, v79
	v_cvt_pk_bf16_f32 v80, v80, v81
	v_cvt_pk_bf16_f32 v81, v82, v83
	global_store_dwordx2 v16, v[52:53], s[8:9]
	global_store_dwordx2 v16, v[56:57], s[8:9] offset:512
	global_store_dwordx2 v16, v[60:61], s[8:9] offset:1024
	global_store_dwordx2 v16, v[64:65], s[8:9] offset:1536
	global_store_dwordx2 v16, v[68:69], s[8:9] offset:2048
	global_store_dwordx2 v16, v[72:73], s[8:9] offset:2560
	global_store_dwordx2 v16, v[76:77], s[8:9] offset:3072
	global_store_dwordx2 v16, v[80:81], s[8:9] offset:3584
	s_branch .LBB0_46
.Lxrow_generic:
	s_lshl_b64 s[4:5], s[2:3], 14
	s_add_u32 s4, s12, s4
	v_lshlrev_b64 v[6:7], 5, v[2:3]
	s_addc_u32 s5, s13, s5
	v_lshl_add_u64 v[6:7], s[4:5], 0, v[6:7]
	s_lshl_b64 s[4:5], s[14:15], 14
	s_lshl_b64 s[8:9], s[2:3], 13
	s_add_u32 s8, s40, s8
	s_addc_u32 s9, s41, s9
	v_lshl_add_u64 v[2:3], v[2:3], 4, s[8:9]
	s_mov_b64 s[8:9], 0x7c00000
	v_lshl_add_u64 v[6:7], v[6:7], 0, 16
	v_lshl_add_u64 v[2:3], v[2:3], 0, s[8:9]
	s_lshl_b64 s[8:9], s[14:15], 13
	s_mov_b64 s[10:11], 0
	s_mov_b64 s[18:19], 0x7fffff
